# weight-conversion items (FF2, out-proj and phase 0) run their loads and transposes at priority 1 on top of the younger-workgroup K-loop raise
# speedup vs baseline: 1.0017x; 1.0017x over previous
.LBB0_66:
	s_or_b64 exec, exec, s[20:21]
	s_waitcnt vmcnt(0)
	ds_write2_b32 v12, v0, v1 offset0:12 offset1:13
	ds_write2_b32 v12, v2, v3 offset0:14 offset1:15
	v_mul_u32_u24_e32 v0, 0x41, v11
	v_lshlrev_b32_e32 v0, 2, v0
	v_lshl_add_u32 v6, v10, 2, v0
	v_add_u32_e32 v5, 0x800, v6
	s_waitcnt lgkmcnt(0)
	s_barrier
	ds_read2_b32 v[2:3], v5 offset0:8 offset1:73
	ds_read2_b32 v[0:1], v6 offset1:65
	v_add_u32_e32 v8, 0x400, v6
	v_add_u32_e32 v12, 0xc00, v6
	v_lshlrev_b32_e32 v136, 1, v11
	s_waitcnt lgkmcnt(1)
	v_cvt_pk_bf16_f32 v4, v2, v3
	ds_read2_b32 v[2:3], v6 offset0:130 offset1:195
	s_waitcnt lgkmcnt(1)
	v_cvt_pk_bf16_f32 v0, v0, v1
	ds_read2_b32 v[6:7], v12 offset0:12 offset1:77
	s_waitcnt lgkmcnt(1)
	v_cvt_pk_bf16_f32 v1, v2, v3
	ds_read2_b32 v[2:3], v5 offset0:138 offset1:203
	s_waitcnt lgkmcnt(1)
	v_cvt_pk_bf16_f32 v6, v6, v7
	s_waitcnt lgkmcnt(0)
	v_cvt_pk_bf16_f32 v5, v2, v3
	ds_read2_b32 v[2:3], v8 offset0:4 offset1:69
	ds_read2_b32 v[8:9], v8 offset0:134 offset1:199
	s_waitcnt lgkmcnt(1)
	v_cvt_pk_bf16_f32 v2, v2, v3
	s_waitcnt lgkmcnt(0)
	v_cvt_pk_bf16_f32 v3, v8, v9
	ds_read2_b32 v[8:9], v12 offset0:142 offset1:207
	s_waitcnt lgkmcnt(0)
	v_cvt_pk_bf16_f32 v7, v8, v9
	v_add_u32_e32 v8, s25, v10
	v_ashrrev_i32_e32 v9, 31, v8
	v_mul_lo_u32 v10, s18, v9
	v_mul_lo_u32 v12, s19, v8
	v_mad_u64_u32 v[8:9], s[18:19], s18, v8, 0
	v_add3_u32 v9, v9, v10, v12
	v_lshl_add_u64 v[8:9], v[8:9], 1, s[16:17]
	s_ashr_i32 s25, s24, 31
	v_lshl_add_u64 v[8:9], s[24:25], 1, v[8:9]
	v_lshl_add_u64 v[8:9], v[8:9], 0, v[136:137]
	global_store_dwordx4 v[8:9], v[0:3], off
	global_store_dwordx4 v[8:9], v[4:7], off offset:16
	s_setprio 0
	s_barrier

.LBB0_73:
	s_or_b64 exec, exec, s[16:17]
	s_waitcnt lgkmcnt(0)
	s_barrier
	ds_read_b32 v0, v170
	s_movk_i32 s16, 0x867
	s_waitcnt lgkmcnt(0)
	v_cmp_lt_i32_e32 vcc, s16, v0
	v_readfirstlane_b32 s20, v0
	s_mov_b64 s[16:17], -1
	s_cbranch_vccnz .LBB0_68
	s_cmpk_gt_i32 s20, 0x367
	s_cbranch_scc0 .LBB0_84
	s_sub_i32 s16, s20, 40
	s_cmpk_lt_u32 s16, 0x440
	s_cselect_b64 s[16:17], -1, 0
	s_and_b64 s[18:19], s[16:17], exec
	s_mov_b32 s18, 0xfc98
	s_cselect_b32 s19, s5, s3
	s_cselect_b32 s18, s18, 0xfb98
	s_cselect_b32 s21, s4, s2
	v_mov_b32_e32 v1, s19
	s_movk_i32 s19, 0x400
	v_mov_b32_e32 v0, s21
	s_cselect_b32 s24, s19, 0x1000
	s_cselect_b32 s19, 4, 6
	s_cselect_b32 s21, 15, 63
	s_cselect_b32 s25, 10, 12
	s_add_i32 s18, s20, s18
	v_mov_b32_e32 v2, v139
	s_and_b32 s23, s18, 0xffff
	s_lshr_b32 s19, s23, s19
	v_ashrrev_i32_e32 v9, 2, v2
	v_lshlrev_b32_e32 v2, 4, v2
	s_lshl_b32 s23, s19, 6
	v_and_b32_e32 v8, 48, v2
	s_and_b32 s18, s21, s18
	v_add_u32_e32 v2, s23, v9
	s_lshl_b32 s21, s18, 6
	v_ashrrev_i32_e32 v3, 31, v2
	v_or_b32_e32 v11, s21, v8
	v_lshlrev_b64 v[2:3], s25, v[2:3]
	s_waitcnt vmcnt(48)
	v_lshl_add_u64 v[6:7], v[2:3], 2, v[0:1]
	v_cmp_gt_u32_e32 vcc, s24, v11
	v_mov_b32_e32 v0, 0
	v_lshlrev_b32_e32 v136, 2, v11
	v_mov_b32_e32 v2, 0
	v_mov_b32_e32 v3, 0
	v_mov_b32_e32 v4, 0
	v_mov_b32_e32 v5, 0
	s_and_saveexec_b64 s[18:19], vcc
	s_cbranch_execz .LBB0_77
	s_setprio 1
	v_lshl_add_u64 v[2:3], v[6:7], 0, v[136:137]
	global_load_dwordx4 v[2:5], v[2:3], off nt

.LBB0_83:
	s_or_b64 exec, exec, s[18:19]
	s_waitcnt vmcnt(0)
	ds_write2_b32 v10, v0, v1 offset0:12 offset1:13
	ds_write2_b32 v10, v2, v3 offset0:14 offset1:15
	v_mul_u32_u24_e32 v0, 0x41, v8
	v_lshlrev_b32_e32 v0, 2, v0
	v_lshl_add_u32 v6, v9, 2, v0
	v_add_u32_e32 v5, 0x800, v6
	s_waitcnt lgkmcnt(0)
	s_barrier
	ds_read2_b32 v[2:3], v5 offset0:8 offset1:73
	ds_read2_b32 v[0:1], v6 offset1:65
	v_add_u32_e32 v10, 0x400, v6
	v_add_u32_e32 v14, 0xc00, v6
	v_readlane_b32 s36, v247, 57
	s_waitcnt lgkmcnt(1)
	v_cvt_pk_bf16_f32 v4, v2, v3
	ds_read2_b32 v[2:3], v6 offset0:130 offset1:195
	s_waitcnt lgkmcnt(1)
	v_cvt_pk_bf16_f32 v0, v0, v1
	ds_read2_b32 v[6:7], v14 offset0:12 offset1:77
	v_readlane_b32 s52, v246, 9
	s_and_b64 s[16:17], s[16:17], exec
	s_waitcnt lgkmcnt(1)
	v_cvt_pk_bf16_f32 v1, v2, v3
	ds_read2_b32 v[2:3], v5 offset0:138 offset1:203
	v_readlane_b32 s50, v246, 7
	v_readlane_b32 s51, v246, 8
	v_readlane_b32 s53, v246, 10
	s_cselect_b32 s16, s51, s53
	s_waitcnt lgkmcnt(0)
	v_cvt_pk_bf16_f32 v5, v2, v3
	ds_read2_b32 v[2:3], v10 offset0:4 offset1:69
	ds_read2_b32 v[10:11], v10 offset0:134 offset1:199
	s_cselect_b32 s17, s50, s52
	v_mov_b32_e32 v12, s17
	v_mov_b32_e32 v13, s16
	s_waitcnt lgkmcnt(1)
	v_cvt_pk_bf16_f32 v2, v2, v3
	s_waitcnt lgkmcnt(0)
	v_cvt_pk_bf16_f32 v3, v10, v11
	ds_read2_b32 v[10:11], v14 offset0:142 offset1:207
	v_add_u32_e32 v9, s21, v9
	s_movk_i32 s36, 0x880
	v_cvt_pk_bf16_f32 v6, v6, v7
	s_lshl_b32 s94, s23, 1
	s_waitcnt lgkmcnt(0)
	v_cvt_pk_bf16_f32 v7, v10, v11
	v_mad_i64_i32 v[10:11], s[16:17], v9, s36, v[12:13]
	v_lshl_add_u64 v[10:11], v[10:11], 0, s[94:95]
	v_lshlrev_b32_e32 v136, 1, v8
	v_lshl_add_u64 v[8:9], v[10:11], 0, v[136:137]
	s_mov_b64 s[16:17], 0
	v_readlane_b32 s37, v247, 58
	v_readlane_b32 s38, v247, 59
	v_readlane_b32 s39, v247, 60
	v_readlane_b32 s40, v247, 61
	v_readlane_b32 s41, v247, 62
	v_readlane_b32 s42, v247, 63
	v_readlane_b32 s43, v246, 0
	v_readlane_b32 s44, v246, 1
	v_readlane_b32 s45, v246, 2
	v_readlane_b32 s46, v246, 3
	v_readlane_b32 s47, v246, 4
	v_readlane_b32 s48, v246, 5
	v_readlane_b32 s49, v246, 6
	v_readlane_b32 s54, v246, 11
	v_readlane_b32 s55, v246, 12
	v_readlane_b32 s56, v246, 13
	v_readlane_b32 s57, v246, 14
	v_readlane_b32 s58, v246, 15
	v_readlane_b32 s59, v246, 16
	v_readlane_b32 s60, v246, 17
	v_readlane_b32 s61, v246, 18
	v_readlane_b32 s62, v246, 19
	v_readlane_b32 s63, v246, 20
	v_readlane_b32 s64, v246, 21
	v_readlane_b32 s65, v246, 22
	v_readlane_b32 s66, v246, 23
	v_readlane_b32 s67, v246, 24
	global_store_dwordx4 v[8:9], v[0:3], off
	global_store_dwordx4 v[8:9], v[4:7], off offset:16
	s_setprio 0
	s_barrier

.LBB0_110:
	v_cvt_f32_u32_e32 v0, s27
	s_sub_i32 s30, 0, s27
	s_abs_i32 s25, s26
	s_ashr_i32 s24, s26, 31
	v_rcp_iflag_f32_e32 v0, v0
	v_mov_b32_e32 v1, v139
	v_mov_b32_e32 v4, 0
	v_mul_f32_e32 v0, 0x4f7ffffe, v0
	v_cvt_u32_f32_e32 v0, v0
	v_ashrrev_i32_e32 v10, 2, v1
	v_lshlrev_b32_e32 v1, 4, v1
	v_and_b32_e32 v11, 48, v1
	v_readfirstlane_b32 s31, v0
	s_mul_i32 s30, s30, s31
	s_mul_hi_u32 s30, s31, s30
	s_add_i32 s31, s31, s30
	s_mul_hi_u32 s30, s25, s31
	s_mul_i32 s31, s30, s27
	s_sub_i32 s25, s25, s31
	s_add_i32 s34, s30, 1
	s_sub_i32 s31, s25, s27
	s_cmp_ge_u32 s25, s27
	s_cselect_b32 s30, s34, s30
	s_cselect_b32 s25, s31, s25
	s_add_i32 s31, s30, 1
	s_cmp_ge_u32 s25, s27
	s_cselect_b32 s25, s31, s30
	s_xor_b32 s25, s25, s24
	s_sub_i32 s24, s25, s24
	s_mul_i32 s25, s24, s27
	s_lshl_b32 s24, s24, 6
	v_add_u32_e32 v0, s24, v10
	s_sub_i32 s25, s26, s25
	v_ashrrev_i32_e32 v3, 31, v0
	v_mad_u64_u32 v[0:1], s[26:27], v0, s23, 0
	v_mov_b32_e32 v2, v1
	s_lshl_b32 s25, s25, 6
	v_mad_u64_u32 v[2:3], s[26:27], v3, s23, v[2:3]
	s_waitcnt vmcnt(48)
	v_or_b32_e32 v6, s25, v11
	v_mov_b32_e32 v1, v2
	v_lshl_add_u64 v[8:9], v[0:1], 2, s[20:21]
	v_cmp_gt_i32_e32 vcc, s23, v6
	v_mov_b32_e32 v0, 0
	v_ashrrev_i32_e32 v7, 31, v6
	v_mov_b32_e32 v2, 0
	v_mov_b32_e32 v3, 0
	v_mov_b32_e32 v5, 0
	s_and_saveexec_b64 s[20:21], vcc
	s_cbranch_execz .LBB0_112
	s_setprio 1
	v_lshl_add_u64 v[2:3], v[6:7], 2, v[8:9]
	global_load_dwordx4 v[2:5], v[2:3], off nt

.LBB0_175:
	s_or_b64 exec, exec, s[16:17]
	s_waitcnt vmcnt(0)
	ds_write2_b32 v12, v0, v1 offset0:12 offset1:13
	ds_write2_b32 v12, v2, v3 offset0:14 offset1:15
	v_mul_u32_u24_e32 v0, 0x41, v11
	v_lshlrev_b32_e32 v0, 2, v0
	v_lshl_add_u32 v6, v10, 2, v0
	v_add_u32_e32 v5, 0x800, v6
	s_waitcnt lgkmcnt(0)
	s_barrier
	ds_read2_b32 v[2:3], v5 offset0:8 offset1:73
	ds_read2_b32 v[0:1], v6 offset1:65
	v_add_u32_e32 v8, 0x400, v6
	v_add_u32_e32 v12, 0xc00, v6
	v_lshlrev_b32_e32 v136, 1, v11
	s_waitcnt lgkmcnt(1)
	v_cvt_pk_bf16_f32 v4, v2, v3
	ds_read2_b32 v[2:3], v6 offset0:130 offset1:195
	s_waitcnt lgkmcnt(1)
	v_cvt_pk_bf16_f32 v0, v0, v1
	ds_read2_b32 v[6:7], v12 offset0:12 offset1:77
	s_waitcnt lgkmcnt(1)
	v_cvt_pk_bf16_f32 v1, v2, v3
	ds_read2_b32 v[2:3], v5 offset0:138 offset1:203
	s_waitcnt lgkmcnt(1)
	v_cvt_pk_bf16_f32 v6, v6, v7
	s_waitcnt lgkmcnt(0)
	v_cvt_pk_bf16_f32 v5, v2, v3
	ds_read2_b32 v[2:3], v8 offset0:4 offset1:69
	ds_read2_b32 v[8:9], v8 offset0:134 offset1:199
	s_waitcnt lgkmcnt(1)
	v_cvt_pk_bf16_f32 v2, v2, v3
	s_waitcnt lgkmcnt(0)
	v_cvt_pk_bf16_f32 v3, v8, v9
	ds_read2_b32 v[8:9], v12 offset0:142 offset1:207
	s_waitcnt lgkmcnt(0)
	v_cvt_pk_bf16_f32 v7, v8, v9
	v_add_u32_e32 v8, s15, v10
	v_ashrrev_i32_e32 v9, 31, v8
	v_mul_lo_u32 v10, s10, v9
	v_mul_lo_u32 v12, s11, v8
	v_mad_u64_u32 v[8:9], s[10:11], s10, v8, 0
	v_add3_u32 v9, v9, v10, v12
	v_lshl_add_u64 v[8:9], v[8:9], 1, s[12:13]
	s_ashr_i32 s15, s14, 31
	v_lshl_add_u64 v[8:9], s[14:15], 1, v[8:9]
	v_lshl_add_u64 v[8:9], v[8:9], 0, v[136:137]
	s_mov_b64 s[10:11], 0
	global_store_dwordx4 v[8:9], v[0:3], off
	global_store_dwordx4 v[8:9], v[4:7], off offset:16
	s_setprio 0
	s_barrier

.LBB0_189:
	v_cvt_f32_u32_e32 v0, s20
	s_sub_i32 s21, 0, s20
	s_abs_i32 s15, s19
	s_ashr_i32 s14, s19, 31
	v_rcp_iflag_f32_e32 v0, v0
	v_mov_b32_e32 v1, v139
	v_mov_b32_e32 v4, 0
	v_mul_f32_e32 v0, 0x4f7ffffe, v0
	v_cvt_u32_f32_e32 v0, v0
	v_ashrrev_i32_e32 v10, 2, v1
	v_lshlrev_b32_e32 v1, 4, v1
	v_and_b32_e32 v11, 48, v1
	v_readfirstlane_b32 s23, v0
	s_mul_i32 s21, s21, s23
	s_mul_hi_u32 s21, s23, s21
	s_add_i32 s23, s23, s21
	s_mul_hi_u32 s21, s15, s23
	s_mul_i32 s23, s21, s20
	s_sub_i32 s15, s15, s23
	s_add_i32 s24, s21, 1
	s_sub_i32 s23, s15, s20
	s_cmp_ge_u32 s15, s20
	s_cselect_b32 s21, s24, s21
	s_cselect_b32 s15, s23, s15
	s_add_i32 s23, s21, 1
	s_cmp_ge_u32 s15, s20
	s_cselect_b32 s15, s23, s21
	s_xor_b32 s15, s15, s14
	s_sub_i32 s14, s15, s14
	s_mul_i32 s15, s14, s20
	s_lshl_b32 s14, s14, 6
	v_add_u32_e32 v0, s14, v10
	v_ashrrev_i32_e32 v3, 31, v0
	v_mad_u64_u32 v[0:1], s[20:21], v0, s18, 0
	s_sub_i32 s15, s19, s15
	v_mov_b32_e32 v2, v1
	s_lshl_b32 s15, s15, 6
	v_mad_u64_u32 v[2:3], s[20:21], v3, s18, v[2:3]
	s_waitcnt vmcnt(48)
	v_or_b32_e32 v6, s15, v11
	v_mov_b32_e32 v1, v2
	v_lshl_add_u64 v[8:9], v[0:1], 2, s[16:17]
	v_cmp_gt_i32_e32 vcc, s18, v6
	v_mov_b32_e32 v0, 0
	v_ashrrev_i32_e32 v7, 31, v6
	v_mov_b32_e32 v2, 0
	v_mov_b32_e32 v3, 0
	v_mov_b32_e32 v5, 0
	s_and_saveexec_b64 s[16:17], vcc
	s_setprio 1
	s_cbranch_execz .LBB0_191
	v_lshl_add_u64 v[2:3], v[6:7], 2, v[8:9]
	global_load_dwordx4 v[2:5], v[2:3], off nt

.LBB0_222:
	s_or_b64 exec, exec, s[0:1]
	s_waitcnt lgkmcnt(0)
	s_barrier
	ds_read_b32 v0, v170
	s_mov_b64 s[0:1], -1
	s_waitcnt lgkmcnt(0)
	v_cmp_le_i32_e32 vcc, s8, v0
	v_readfirstlane_b32 s16, v0
	s_cbranch_vccnz .LBB0_217
	s_cmpk_gt_i32 s16, 0x59f
	s_cbranch_scc0 .LBB0_233
	s_add_i32 s0, s16, 0xfffffda0
	s_cmpk_lt_u32 s0, 0x440
	s_cselect_b64 s[0:1], -1, 0
	s_and_b64 s[2:3], s[0:1], exec
	s_mov_b32 s2, 0xfa60
	s_cselect_b32 s3, s12, s11
	s_cselect_b32 s2, s2, 0xf960
	s_cselect_b32 s4, s91, s9
	v_mov_b32_e32 v1, s3
	s_movk_i32 s3, 0x400
	v_mov_b32_e32 v0, s4
	s_cselect_b32 s6, s3, 0x1000
	s_cselect_b32 s3, 4, 6
	s_cselect_b32 s4, 15, 63
	s_cselect_b32 s7, 10, 12
	s_add_i32 s2, s16, s2
	v_mov_b32_e32 v2, v139
	s_and_b32 s5, s2, 0xffff
	s_lshr_b32 s3, s5, s3
	v_ashrrev_i32_e32 v9, 2, v2
	v_lshlrev_b32_e32 v2, 4, v2
	s_lshl_b32 s5, s3, 6
	v_and_b32_e32 v8, 48, v2
	s_and_b32 s2, s4, s2
	v_add_u32_e32 v2, s5, v9
	s_lshl_b32 s4, s2, 6
	v_ashrrev_i32_e32 v3, 31, v2
	v_or_b32_e32 v11, s4, v8
	v_lshlrev_b64 v[2:3], s7, v[2:3]
	s_waitcnt vmcnt(48)
	v_lshl_add_u64 v[6:7], v[2:3], 2, v[0:1]
	v_cmp_gt_u32_e32 vcc, s6, v11
	v_mov_b32_e32 v0, 0
	v_lshlrev_b32_e32 v136, 2, v11
	v_mov_b32_e32 v2, 0
	v_mov_b32_e32 v3, 0
	v_mov_b32_e32 v4, 0
	v_mov_b32_e32 v5, 0
	s_and_saveexec_b64 s[2:3], vcc
	s_setprio 1
	s_cbranch_execz .LBB0_226
	v_lshl_add_u64 v[2:3], v[6:7], 0, v[136:137]
	global_load_dwordx4 v[2:5], v[2:3], off nt

.LBB0_232:
	s_or_b64 exec, exec, s[2:3]
	s_waitcnt vmcnt(0)
	ds_write2_b32 v10, v0, v1 offset0:12 offset1:13
	ds_write2_b32 v10, v2, v3 offset0:14 offset1:15
	v_mul_u32_u24_e32 v0, 0x41, v8
	v_lshlrev_b32_e32 v0, 2, v0
	v_lshl_add_u32 v6, v9, 2, v0
	v_add_u32_e32 v5, 0x800, v6
	s_waitcnt lgkmcnt(0)
	s_barrier
	ds_read2_b32 v[2:3], v5 offset0:8 offset1:73
	ds_read2_b32 v[0:1], v6 offset1:65
	v_add_u32_e32 v10, 0x400, v6
	v_readlane_b32 s36, v246, 9
	v_add_u32_e32 v14, 0xc00, v6
	s_waitcnt lgkmcnt(1)
	v_cvt_pk_bf16_f32 v4, v2, v3
	ds_read2_b32 v[2:3], v6 offset0:130 offset1:195
	s_waitcnt lgkmcnt(1)
	v_cvt_pk_bf16_f32 v0, v0, v1
	v_readlane_b32 s40, v246, 13
	v_readlane_b32 s41, v246, 14
	v_readlane_b32 s42, v246, 15
	s_waitcnt lgkmcnt(0)
	v_cvt_pk_bf16_f32 v1, v2, v3
	ds_read2_b32 v[2:3], v5 offset0:138 offset1:203
	v_readlane_b32 s43, v246, 16
	v_readlane_b32 s44, v246, 17
	v_readlane_b32 s45, v246, 18
	v_readlane_b32 s46, v246, 19
	s_waitcnt lgkmcnt(0)
	v_cvt_pk_bf16_f32 v5, v2, v3
	ds_read2_b32 v[2:3], v10 offset0:4 offset1:69
	ds_read2_b32 v[10:11], v10 offset0:134 offset1:199
	v_readlane_b32 s47, v246, 20
	v_readlane_b32 s48, v246, 21
	v_readlane_b32 s49, v246, 22
	v_readlane_b32 s50, v246, 23
	v_readlane_b32 s51, v246, 24
	s_waitcnt lgkmcnt(1)
	v_cvt_pk_bf16_f32 v2, v2, v3
	ds_read2_b32 v[6:7], v14 offset0:12 offset1:77
	s_waitcnt lgkmcnt(1)
	v_cvt_pk_bf16_f32 v3, v10, v11
	ds_read2_b32 v[10:11], v14 offset0:142 offset1:207
	v_readlane_b32 s40, v247, 57
	s_and_b64 s[0:1], s[0:1], exec
	v_readlane_b32 s37, v246, 10
	v_readlane_b32 s54, v246, 7
	v_readlane_b32 s55, v246, 8
	s_cselect_b32 s0, s55, s37
	s_cselect_b32 s1, s54, s36
	v_mov_b32_e32 v12, s1
	v_mov_b32_e32 v13, s0
	v_add_u32_e32 v9, s4, v9
	s_movk_i32 s36, 0x880
	s_waitcnt lgkmcnt(1)
	v_cvt_pk_bf16_f32 v6, v6, v7
	s_waitcnt lgkmcnt(0)
	v_cvt_pk_bf16_f32 v7, v10, v11
	v_mad_i64_i32 v[10:11], s[0:1], v9, s36, v[12:13]
	s_lshl_b32 s94, s5, 1
	v_lshl_add_u64 v[10:11], v[10:11], 0, s[94:95]
	v_lshlrev_b32_e32 v136, 1, v8
	v_lshl_add_u64 v[8:9], v[10:11], 0, v[136:137]
	s_mov_b64 s[0:1], 0
	v_readlane_b32 s38, v246, 11
	v_readlane_b32 s39, v246, 12
	v_readlane_b32 s41, v247, 58
	v_readlane_b32 s42, v247, 59
	v_readlane_b32 s43, v247, 60
	v_readlane_b32 s44, v247, 61
	v_readlane_b32 s45, v247, 62
	v_readlane_b32 s46, v247, 63
	v_readlane_b32 s47, v246, 0
	v_readlane_b32 s48, v246, 1
	v_readlane_b32 s49, v246, 2
	v_readlane_b32 s50, v246, 3
	v_readlane_b32 s51, v246, 4
	v_readlane_b32 s52, v246, 5
	v_readlane_b32 s53, v246, 6
	global_store_dwordx4 v[8:9], v[0:3], off
	global_store_dwordx4 v[8:9], v[4:7], off offset:16
	s_setprio 0
	s_barrier

.LBB0_1163:
	s_and_b32 s8, 0xffff, s13
	v_cvt_f32_u32_e32 v0, s8
	s_and_b32 s8, s12, 0xffff
	v_cvt_f32_u32_e32 v1, s8
	v_mov_b32_e32 v3, v139
	s_waitcnt lgkmcnt(0)
	v_rcp_iflag_f32_e32 v2, v0
	v_mov_b32_e32 v5, 0
	v_ashrrev_i32_e32 v8, 2, v3
	v_mul_f32_e32 v2, v1, v2
	v_trunc_f32_e32 v2, v2
	v_cvt_u32_f32_e32 v4, v2
	v_fma_f32 v1, -v2, v0, v1
	v_cmp_ge_f32_e64 s[8:9], |v1|, v0
	s_cmp_lg_u64 s[8:9], 0
	v_readfirstlane_b32 s8, v4
	s_addc_u32 s8, s8, 0
	s_and_b32 s14, s8, 0xffff
	s_mul_i32 s8, s8, s13
	s_sub_i32 s8, s12, s8
	s_lshl_b32 s8, s8, 6
	v_lshlrev_b32_e32 v0, 4, v3
	s_and_b32 s9, s8, 0xffc0
	s_lshl_b32 s8, s14, 6
	v_and_b32_e32 v9, 48, v0
	v_add_u32_e32 v0, s8, v8
	v_ashrrev_i32_e32 v3, 31, v0
	v_mad_u64_u32 v[0:1], s[12:13], v0, s11, 0
	v_mov_b32_e32 v2, v1
	v_mad_u64_u32 v[2:3], s[12:13], v3, s11, v[2:3]
	v_or_b32_e32 v10, s9, v9
	v_mov_b32_e32 v1, v2
	s_waitcnt vmcnt(48)
	v_lshl_add_u64 v[6:7], v[0:1], 2, s[6:7]
	v_cmp_gt_u32_e32 vcc, s11, v10
	v_mov_b32_e32 v0, 0
	v_lshlrev_b32_e32 v136, 2, v10
	v_mov_b32_e32 v2, 0
	v_mov_b32_e32 v3, 0
	v_mov_b32_e32 v4, 0
	s_setprio 1
	s_and_saveexec_b64 s[6:7], vcc
	s_cbranch_execz .LBB0_1165
	v_lshl_add_u64 v[2:3], v[6:7], 0, v[136:137]
	global_load_dwordx4 v[2:5], v[2:3], off nt

.LBB0_1171:
	s_or_b64 exec, exec, s[6:7]
	s_waitcnt vmcnt(0)
	ds_write2_b32 v11, v0, v1 offset0:12 offset1:13
	ds_write2_b32 v11, v2, v3 offset0:14 offset1:15
	v_mul_u32_u24_e32 v0, 0x41, v9
	v_lshlrev_b32_e32 v0, 2, v0
	v_lshl_add_u32 v6, v8, 2, v0
	v_add_u32_e32 v5, 0x800, v6
	s_waitcnt lgkmcnt(0)
	s_barrier
	ds_read2_b32 v[2:3], v5 offset0:8 offset1:73
	ds_read2_b32 v[0:1], v6 offset1:65
	v_add_u32_e32 v10, 0x400, v6
	v_add_u32_e32 v12, 0xc00, v6
	v_add_u32_e32 v8, s9, v8
	s_waitcnt lgkmcnt(1)
	v_cvt_pk_bf16_f32 v4, v2, v3
	ds_read2_b32 v[2:3], v6 offset0:130 offset1:195
	s_waitcnt lgkmcnt(1)
	v_cvt_pk_bf16_f32 v0, v0, v1
	ds_read2_b32 v[6:7], v12 offset0:12 offset1:77
	v_mul_lo_u32 v13, s5, v8
	s_lshl_b32 s94, s8, 1
	s_waitcnt lgkmcnt(1)
	v_cvt_pk_bf16_f32 v1, v2, v3
	ds_read2_b32 v[2:3], v5 offset0:138 offset1:203
	s_waitcnt lgkmcnt(1)
	v_cvt_pk_bf16_f32 v6, v6, v7
	v_lshlrev_b32_e32 v136, 1, v9
	s_waitcnt lgkmcnt(0)
	v_cvt_pk_bf16_f32 v5, v2, v3
	ds_read2_b32 v[2:3], v10 offset0:4 offset1:69
	ds_read2_b32 v[10:11], v10 offset0:134 offset1:199
	s_waitcnt lgkmcnt(1)
	v_cvt_pk_bf16_f32 v2, v2, v3
	s_waitcnt lgkmcnt(0)
	v_cvt_pk_bf16_f32 v3, v10, v11
	ds_read2_b32 v[10:11], v12 offset0:142 offset1:207
	s_waitcnt lgkmcnt(0)
	v_cvt_pk_bf16_f32 v7, v10, v11
	v_ashrrev_i32_e32 v10, 31, v8
	v_mul_lo_u32 v12, s4, v10
	v_mad_u64_u32 v[10:11], s[4:5], s4, v8, 0
	v_add3_u32 v11, v11, v12, v13
	v_lshl_add_u64 v[10:11], v[10:11], 1, s[2:3]
	v_lshl_add_u64 v[10:11], v[10:11], 0, s[94:95]
	v_lshl_add_u64 v[8:9], v[10:11], 0, v[136:137]
	s_mov_b64 s[4:5], 0
	s_mov_b64 s[2:3], -1
	global_store_dwordx4 v[8:9], v[0:3], off
	global_store_dwordx4 v[8:9], v[4:7], off offset:16
	s_setprio 0
	s_barrier
